# FFN2 gate-up tail takes one 64-row final-row-pass chunk per workgroup (was up to two) so all workgroups share the tail
# baseline (speedup 1.0000x reference)
; #define LAS __attribute__((address_space(3)))
;     for (int n = 0; n < max_chunks; ++n) {
;         if (tid == 0) MISC[0] = (int)atomicAdd(ctr, 1u);
;         __syncthreads();
;         const int c = __builtin_amdgcn_readfirstlane(MISC[0]);
;         __syncthreads();
;         if (c >= RP_CHUNKS) break;
; __global__ void __launch_bounds__(512, 2) fwd_kernel(Params p) {
;     ...
;                                  else row_pass_chunks<3>(p, (LAS int*)(lds + MISC_LDS), CTL + 7, 2, tid, wave, lane, p.in[24], nullptr, Breg, nullptr, 0.5f); }
.LBB0_1715:
	s_mov_b64 s[48:49], -1
